# v052_attnorder
# speedup vs baseline: 1.0051x; 1.0016x over previous
; __device__ __forceinline__ void attn_wave_item(const Params& p, int witem, const int tidx) {
;     ...
;     u32x4 vf[8], kn[8];
;     {
;       const int tn = tile > 0 ? tile - 1 : 0;
;       const char* vp = vbase + (size_t)tile * 8192;
;       const char* kp = kbase + (size_t)tn * 8192;
; #pragma unroll
;       for (int i = 0; i < 8; ++i) vf[i] = *reinterpret_cast<const u32x4*>(vp + i * 1024);
; #pragma unroll
;       for (int ks = 0; ks < 8; ++ks) kn[ks] = *reinterpret_cast<const u32x4*>(kp + ks * 1024);
;     }
;     __builtin_amdgcn_sched_barrier(0);
;     f32x16 S, S2;
; #pragma unroll
;     for (int i = 0; i < 16; ++i) { S[i] = 0.f; S2[i] = 0.f; }
; #pragma unroll
;     for (int ks = 0; ks < 8; ks += 2) {
;       u32x4 qa = *reinterpret_cast<const u32x4*>(qlds + ks * 1024);
;       u32x4 qb = *reinterpret_cast<const u32x4*>(qlds + (ks + 1) * 1024);
;       S = __builtin_amdgcn_mfma_f32_32x32x16_bf16(as_bf16x8(kf[ks]), as_bf16x8(qa), S, 0, 0, 0);
;       S2 = __builtin_amdgcn_mfma_f32_32x32x16_bf16(as_bf16x8(kf[ks + 1]), as_bf16x8(qb), S2, 0, 0, 0);
;     }
; #pragma unroll
;     for (int i = 0; i < 16; ++i) S[i] += S2[i];
;     const bool diag = (tile == qt);
;     float be[16], om[16];
; #pragma unroll
;     for (int r = 0; r < 16; ++r) {
;       float z = S[r];
;       float e = __builtin_amdgcn_exp2f(-fabsf(z));
;       float rr = __builtin_amdgcn_rcpf(1.f + e);
;       float sm = e * rr;
;       int kl = (r & 3) + 8 * (r >> 2) + 4 * half;
;       bool v = !diag || (kl < n);
;       bool pos = z >= 0.f;
;       be[r] = v ? (pos ? rr : sm) : 0.f;
;       om[r] = v ? (pos ? sm : rr) : 1.f;
;     }
.LBB0_119:
	ds_read_b128 v[226:229], v173
	ds_read_b128 v[84:87], v173 offset:1024
	ds_read_b128 v[204:207], v173 offset:2048
	ds_read_b128 v[222:225], v173 offset:3072
	v_sub_u32_e64 v162, v169, 1 clamp
	s_waitcnt vmcnt(0)
	v_mov_b64_e32 v[198:199], v[112:113]
	v_mov_b64_e32 v[202:203], v[108:109]
	v_mov_b64_e32 v[80:81], v[102:103]
	v_mov_b64_e32 v[64:65], v[98:99]
	v_mov_b64_e32 v[196:197], v[110:111]
	v_mov_b64_e32 v[200:201], v[106:107]
	v_mov_b64_e32 v[82:83], v[104:105]
	v_mov_b64_e32 v[66:67], v[100:101]
	v_mov_b64_e32 v[182:183], v[128:129]
	v_mov_b64_e32 v[186:187], v[124:125]
	v_mov_b64_e32 v[190:191], v[120:121]
	v_mov_b64_e32 v[194:195], v[116:117]
	v_mov_b64_e32 v[180:181], v[126:127]
	v_mov_b64_e32 v[184:185], v[122:123]
	v_mov_b64_e32 v[188:189], v[118:119]
	v_mov_b64_e32 v[192:193], v[114:115]
	s_cmp_lg_u32 s48, 0
	s_cselect_b64 s[50:51], -1, 0
	s_waitcnt lgkmcnt(3)
	s_setprio 1
	v_mfma_f32_32x32x16_bf16 v[64:79], v[64:67], v[226:229], 0
	s_or_b64 s[44:45], s[6:7], s[50:51]
	s_waitcnt lgkmcnt(2)
	v_mfma_f32_32x32x16_bf16 v[80:95], v[80:83], v[84:87], 0
	s_waitcnt lgkmcnt(1)
	v_mfma_f32_32x32x16_bf16 v[64:79], v[200:203], v[204:207], v[64:79]
	s_waitcnt lgkmcnt(0)
	v_mfma_f32_32x32x16_bf16 v[80:95], v[196:199], v[222:225], v[80:95]
	ds_read_b128 v[196:199], v173 offset:4096
	ds_read_b128 v[200:203], v173 offset:5120
	s_waitcnt lgkmcnt(1)
	v_mfma_f32_32x32x16_bf16 v[64:79], v[192:195], v[196:199], v[64:79]
	s_waitcnt lgkmcnt(0)
	v_mfma_f32_32x32x16_bf16 v[80:95], v[188:191], v[200:203], v[80:95]
	ds_read_b128 v[188:191], v173 offset:6144
	ds_read_b128 v[192:195], v173 offset:7168
	s_waitcnt lgkmcnt(1)
	v_mfma_f32_32x32x16_bf16 v[64:79], v[184:187], v[188:191], v[64:79]
	s_waitcnt lgkmcnt(0)
	v_mfma_f32_32x32x16_bf16 v[80:95], v[180:183], v[192:195], v[80:95]
	s_setprio 0
	v_lshl_add_u64 v[246:247], v[174:175], 0, s[48:49]
	s_mov_b32 s42, 0x20900000
	v_add_co_u32_e64 v248, s[42:43], s42, v246
	s_nop 1
	v_addc_co_u32_e64 v249, s[42:43], 0, v247, s[42:43]
	s_mov_b32 s42, 0x20901000
	v_add_co_u32_e64 v246, s[42:43], s42, v246
	s_nop 1
	v_addc_co_u32_e64 v247, s[42:43], 0, v247, s[42:43]
	global_load_dwordx4 v[154:157], v[248:249], off offset:1024
	global_load_dwordx4 v[150:153], v[248:249], off offset:2048
	global_load_dwordx4 v[142:145], v[248:249], off offset:3072
	global_load_dwordx4 v[158:161], v[246:247], off offset:-4096
	global_load_dwordx4 v[146:149], v[246:247], off
	global_load_dwordx4 v[138:141], v[246:247], off offset:1024
	global_load_dwordx4 v[134:137], v[246:247], off offset:2048
	global_load_dwordx4 v[130:133], v[246:247], off offset:3072
	v_lshlrev_b64 v[250:251], 13, v[162:163]
	v_lshl_add_u64 v[250:251], v[170:171], 0, v[250:251]
	v_add_co_u32_e64 v252, s[42:43], s58, v250
	s_nop 1
	v_addc_co_u32_e64 v253, s[42:43], 0, v251, s[42:43]
	global_load_dwordx4 v[98:101], v[250:251], off
	global_load_dwordx4 v[102:105], v[250:251], off offset:1024
	global_load_dwordx4 v[106:109], v[250:251], off offset:2048
	global_load_dwordx4 v[110:113], v[250:251], off offset:3072
	global_load_dwordx4 v[114:117], v[252:253], off
	global_load_dwordx4 v[118:121], v[252:253], off offset:1024
	global_load_dwordx4 v[122:125], v[252:253], off offset:2048
	global_load_dwordx4 v[126:129], v[252:253], off offset:3072
	s_nop 0
	v_add_f32_e32 v64, v64, v80
	v_exp_f32_e64 v80, -|v64|
	v_add_f32_e32 v65, v65, v81
	v_add_f32_e32 v66, v66, v82
	v_exp_f32_e64 v82, -|v65|
	v_add_f32_e32 v81, 1.0, v80
	v_rcp_f32_e32 v81, v81
	v_add_f32_e32 v67, v67, v83
	v_add_f32_e32 v83, 1.0, v82
	v_cmp_le_f32_e64 s[42:43], 0, v64
	v_mul_f32_e32 v80, v80, v81
	v_rcp_f32_e32 v83, v83
	v_cndmask_b32_e64 v64, v80, v81, s[42:43]
	v_add_f32_e32 v68, v68, v84
	v_cndmask_b32_e64 v84, 0, v64, s[44:45]
	v_cndmask_b32_e64 v64, v81, v80, s[42:43]
	v_exp_f32_e64 v81, -|v66|
	v_cndmask_b32_e64 v80, 1.0, v64, s[44:45]
	v_mul_f32_e32 v64, v82, v83
	v_cmp_le_f32_e64 s[42:43], 0, v65
	s_or_b64 s[44:45], s[8:9], s[50:51]
	v_add_f32_e32 v69, v69, v85
	v_cndmask_b32_e64 v65, v64, v83, s[42:43]
	v_cndmask_b32_e64 v64, v83, v64, s[42:43]
	v_cndmask_b32_e64 v82, 0, v65, s[44:45]
	v_add_f32_e32 v65, 1.0, v81
	v_cndmask_b32_e64 v83, 1.0, v64, s[44:45]
	v_exp_f32_e64 v64, -|v67|
	v_rcp_f32_e32 v65, v65
	v_cmp_le_f32_e64 s[42:43], 0, v66
	s_or_b64 s[44:45], s[10:11], s[50:51]
	v_add_f32_e32 v85, 1.0, v64
	v_mul_f32_e32 v81, v81, v65
	v_rcp_f32_e32 v85, v85
	v_cndmask_b32_e64 v66, v81, v65, s[42:43]
	v_cndmask_b32_e64 v65, v65, v81, s[42:43]
	v_cndmask_b32_e64 v81, 1.0, v65, s[44:45]
	v_exp_f32_e64 v65, -|v68|
	v_mul_f32_e32 v64, v64, v85
	v_cmp_le_f32_e64 s[42:43], 0, v67
	v_exp_f32_e64 v67, -|v69|
	v_add_f32_e32 v70, v70, v86
	v_cndmask_b32_e64 v86, 0, v66, s[44:45]
	v_cndmask_b32_e64 v66, v64, v85, s[42:43]
	s_or_b64 s[44:45], s[12:13], s[50:51]
	v_add_f32_e32 v71, v71, v87
	v_cndmask_b32_e64 v87, 0, v66, s[44:45]
	v_add_f32_e32 v66, 1.0, v65
	v_rcp_f32_e32 v66, v66
	v_cndmask_b32_e64 v64, v85, v64, s[42:43]
	v_cmp_le_f32_e64 s[42:43], 0, v68
	v_add_f32_e32 v68, 1.0, v67
	v_rcp_f32_e32 v68, v68
	v_cndmask_b32_e64 v85, 1.0, v64, s[44:45]
	v_mul_f32_e32 v64, v65, v66
	v_cndmask_b32_e64 v65, v64, v66, s[42:43]
	s_or_b64 s[44:45], s[14:15], s[50:51]
	v_add_f32_e32 v72, v72, v88
	v_cndmask_b32_e64 v88, 0, v65, s[44:45]
	v_mul_f32_e32 v65, v67, v68
	v_exp_f32_e64 v67, -|v70|
	v_cndmask_b32_e64 v64, v66, v64, s[42:43]
	v_cmp_le_f32_e64 s[42:43], 0, v69
	v_cndmask_b32_e64 v64, 1.0, v64, s[44:45]
	s_or_b64 s[44:45], s[16:17], s[50:51]
	v_cndmask_b32_e64 v66, v65, v68, s[42:43]
	v_add_f32_e32 v73, v73, v89
	v_cndmask_b32_e64 v89, 0, v66, s[44:45]
	v_add_f32_e32 v66, 1.0, v67
; __device__ __forceinline__ void attn_wave_item(const Params& p, int witem, const int tidx) {
;     ...
;     for (int r = 0; r < 16; ++r) {
;       float z = S[r];
;       float e = __builtin_amdgcn_exp2f(-fabsf(z));
;       float rr = __builtin_amdgcn_rcpf(1.f + e);
;       float sm = e * rr;
;       int kl = (r & 3) + 8 * (r >> 2) + 4 * half;
;       bool v = !diag || (kl < n);
;       bool pos = z >= 0.f;
;       be[r] = v ? (pos ? rr : sm) : 0.f;
;       om[r] = v ? (pos ? sm : rr) : 1.f;
;     }
;     float gp[4], pgp[4];
; #pragma unroll
;     for (int gi = 0; gi < 4; ++gi) {
;       gp[gi] = (om[4 * gi] * om[4 * gi + 1]) * (om[4 * gi + 2] * om[4 * gi + 3]);
;       pgp[gi] = __shfl_xor(gp[gi], 32, 64);
;     }
;     float w[16];
;     float run = R;
; #pragma unroll
;     ...
;       float a = (half == 0) ? (run * pgp[gi]) : run;
; #pragma unroll
;       for (int r = 3; r >= 0; --r) {
;         int ri = 4 * gi + r;
;         w[ri] = be[ri] * a;
;         a *= om[ri];
;       }
;       run *= gp[gi] * pgp[gi];
;     }
;     R = run;
;     __builtin_amdgcn_sched_barrier(0);
;     bf16x8 pf[2];
; #pragma unroll
;     for (int m = 0; m < 2; ++m) {
;       u32x4 t;
;       t.x = pack2(w[8 * m + 0], w[8 * m + 1]);
;       t.y = pack2(w[8 * m + 2], w[8 * m + 3]);
;       t.z = pack2(w[8 * m + 4], w[8 * m + 5]);
;       t.w = pack2(w[8 * m + 6], w[8 * m + 7]);
;       pf[m] = as_bf16x8(t);
;     }
; #pragma unroll
;     for (int dt = 0; dt < 4; ++dt)
; #pragma unroll
;       for (int m = 0; m < 2; ++m) O[dt] = __builtin_amdgcn_mfma_f32_32x32x16_bf16(as_bf16x8(vf[dt * 2 + m]), pf[m], O[dt], 0, 0, 0);
;     if (__all(R < 1.17549435e-38f)) break;
;     __builtin_amdgcn_sched_barrier(0);
; #pragma unroll
;     for (int i = 0; i < 8; ++i) kf[i] = kn[i];
	v_cndmask_b32_e64 v65, v68, v65, s[42:43]
	v_rcp_f32_e32 v69, v66
	v_cndmask_b32_e64 v66, 1.0, v65, s[44:45]
	v_exp_f32_e64 v65, -|v71|
	v_cmp_le_f32_e64 s[42:43], 0, v70
	v_mul_f32_e32 v67, v67, v69
	s_or_b64 s[44:45], s[18:19], s[50:51]
	v_add_f32_e32 v70, 1.0, v65
	v_rcp_f32_e32 v70, v70
	v_cndmask_b32_e64 v68, v67, v69, s[42:43]
	v_cndmask_b32_e64 v67, v69, v67, s[42:43]
	v_cndmask_b32_e64 v176, 1.0, v67, s[44:45]
	v_exp_f32_e64 v67, -|v72|
	v_mul_f32_e32 v65, v65, v70
	v_cmp_le_f32_e64 s[42:43], 0, v71
	v_add_f32_e32 v74, v74, v90
	v_cndmask_b32_e64 v90, 0, v68, s[44:45]
	v_cndmask_b32_e64 v68, v65, v70, s[42:43]
	s_or_b64 s[44:45], s[20:21], s[50:51]
	v_cndmask_b32_e64 v71, 0, v68, s[44:45]
	v_add_f32_e32 v68, 1.0, v67
	v_cndmask_b32_e64 v65, v70, v65, s[42:43]
	v_rcp_f32_e32 v69, v68
	v_cndmask_b32_e64 v68, 1.0, v65, s[44:45]
	v_exp_f32_e64 v65, -|v73|
	v_cmp_le_f32_e64 s[42:43], 0, v72
	v_mul_f32_e32 v67, v67, v69
	s_or_b64 s[44:45], s[22:23], s[50:51]
	v_add_f32_e32 v72, 1.0, v65
	v_rcp_f32_e32 v72, v72
	v_cndmask_b32_e64 v70, v67, v69, s[42:43]
	v_cndmask_b32_e64 v67, v69, v67, s[42:43]
	v_cmp_le_f32_e64 s[42:43], 0, v73
	v_mul_f32_e32 v65, v65, v72
	v_add_f32_e32 v75, v75, v91
	v_cndmask_b32_e64 v91, 0, v70, s[44:45]
	v_cndmask_b32_e64 v67, 1.0, v67, s[44:45]
	v_exp_f32_e64 v69, -|v74|
	v_cndmask_b32_e64 v70, v65, v72, s[42:43]
	s_or_b64 s[44:45], s[24:25], s[50:51]
	v_cndmask_b32_e64 v65, v72, v65, s[42:43]
	v_add_f32_e32 v77, v77, v93
	v_cndmask_b32_e64 v93, 1.0, v65, s[44:45]
	v_exp_f32_e64 v65, -|v75|
	v_add_f32_e32 v76, v76, v92
	v_cndmask_b32_e64 v92, 0, v70, s[44:45]
	v_add_f32_e32 v70, 1.0, v69
	v_rcp_f32_e32 v70, v70
	v_add_f32_e32 v73, 1.0, v65
	v_rcp_f32_e32 v73, v73
	v_cmp_le_f32_e64 s[42:43], 0, v74
	v_mul_f32_e32 v69, v69, v70
	s_or_b64 s[44:45], s[26:27], s[50:51]
	v_cndmask_b32_e64 v72, v69, v70, s[42:43]
	v_cndmask_b32_e64 v69, v70, v69, s[42:43]
	v_mul_f32_e32 v65, v65, v73
	v_cmp_le_f32_e64 s[42:43], 0, v75
	v_add_f32_e32 v78, v78, v94
	v_add_f32_e32 v79, v79, v95
	v_cndmask_b32_e64 v94, 0, v72, s[44:45]
	v_cndmask_b32_e64 v95, 1.0, v69, s[44:45]
	v_exp_f32_e64 v69, -|v76|
	v_cndmask_b32_e64 v70, v65, v73, s[42:43]
	s_or_b64 s[44:45], s[28:29], s[50:51]
	v_cndmask_b32_e64 v65, v73, v65, s[42:43]
	v_cndmask_b32_e64 v179, 1.0, v65, s[44:45]
	v_exp_f32_e64 v65, -|v77|
	v_cndmask_b32_e64 v162, 0, v70, s[44:45]
	v_add_f32_e32 v70, 1.0, v69
	v_rcp_f32_e32 v70, v70
	v_add_f32_e32 v73, 1.0, v65
	v_rcp_f32_e32 v73, v73
	v_cmp_le_f32_e64 s[42:43], 0, v76
	v_mul_f32_e32 v69, v69, v70
	s_or_b64 s[44:45], s[30:31], s[50:51]
	v_cndmask_b32_e64 v72, v69, v70, s[42:43]
	v_cndmask_b32_e64 v69, v70, v69, s[42:43]
	v_mul_f32_e32 v65, v65, v73
	v_cmp_le_f32_e64 s[42:43], 0, v77
	v_cndmask_b32_e64 v74, 0, v72, s[44:45]
	v_cndmask_b32_e64 v69, 1.0, v69, s[44:45]
	v_exp_f32_e64 v70, -|v78|
	v_cndmask_b32_e64 v72, v65, v73, s[42:43]
	s_or_b64 s[44:45], s[34:35], s[50:51]
	v_cndmask_b32_e64 v65, v73, v65, s[42:43]
	v_cndmask_b32_e64 v73, 1.0, v65, s[44:45]
	v_exp_f32_e64 v65, -|v79|
	v_cndmask_b32_e64 v75, 0, v72, s[44:45]
	v_add_f32_e32 v72, 1.0, v70
	v_rcp_f32_e32 v72, v72
	v_add_f32_e32 v77, 1.0, v65
	v_rcp_f32_e32 v77, v77
	v_cmp_le_f32_e64 s[42:43], 0, v78
	v_mul_f32_e32 v70, v70, v72
	s_or_b64 s[44:45], s[36:37], s[50:51]
	v_cndmask_b32_e64 v76, v70, v72, s[42:43]
	v_cndmask_b32_e64 v70, v72, v70, s[42:43]
	v_mul_f32_e32 v65, v65, v77
	v_cmp_le_f32_e64 s[42:43], 0, v79
	v_cndmask_b32_e64 v76, 0, v76, s[44:45]
	v_cndmask_b32_e64 v78, 1.0, v70, s[44:45]
	v_cndmask_b32_e64 v70, v65, v77, s[42:43]
	s_or_b64 s[44:45], s[38:39], s[50:51]
	v_cndmask_b32_e64 v65, v77, v65, s[42:43]
	v_cndmask_b32_e64 v77, 1.0, v65, s[44:45]
	v_mul_f32_e32 v65, v69, v73
	v_mul_f32_e32 v69, v78, v77
	v_mul_f32_e32 v69, v65, v69
	v_cndmask_b32_e64 v79, 0, v70, s[44:45]
	v_mul_f32_e32 v70, v80, v83
	ds_bpermute_b32 v80, v178, v69
	v_mul_f32_e32 v65, v67, v93
	v_mul_f32_e32 v67, v95, v179
	v_mul_f32_e32 v65, v65, v67
	ds_bpermute_b32 v67, v178, v65
	s_waitcnt lgkmcnt(1)
	v_mul_f32_e32 v180, v177, v80
	v_cndmask_b32_e32 v180, v177, v180, vcc
	v_mul_f32_e32 v77, v180, v77
	v_mul_f32_e32 v76, v76, v77
	v_mul_f32_e32 v77, v78, v77
	v_mul_f32_e32 v73, v73, v77
	v_mul_f32_e32 v69, v69, v80
	v_mul_f32_e32 v78, v75, v77
	v_mul_f32_e32 v77, v74, v73
	v_pk_mul_f32 v[74:75], v[176:177], v[68:69]
	s_waitcnt lgkmcnt(0)
	v_pk_mul_f32 v[64:65], v[64:65], v[66:67]
	v_mul_f32_e32 v67, v75, v67
	v_pk_mul_f32 v[64:65], v[64:65], v[74:75]
	ds_bpermute_b32 v73, v178, v64
	v_cndmask_b32_e32 v67, v75, v67, vcc
	v_mul_f32_e32 v74, v162, v67
	v_mul_f32_e32 v67, v179, v67
	v_mul_f32_e32 v75, v94, v67
	v_mul_f32_e32 v67, v95, v67
	v_mul_f32_e32 v80, v92, v67
	v_mul_f32_e32 v67, v93, v67
	v_mul_f32_e32 v91, v91, v67
	s_waitcnt lgkmcnt(0)
	v_mul_f32_e32 v67, v65, v73
	v_cndmask_b32_e32 v67, v65, v67, vcc
	v_mul_f32_e32 v72, v81, v85
	v_mul_f32_e32 v92, v71, v67
	v_mov_b32_e32 v71, v64
	v_mul_f32_e32 v67, v68, v67
	v_pk_mul_f32 v[68:69], v[70:71], v[72:73]
	ds_bpermute_b32 v64, v178, v68
	v_mul_f32_e32 v90, v90, v67
	v_mul_f32_e32 v67, v176, v67
	v_mul_f32_e32 v70, v89, v67
	v_mul_f32_e32 v66, v66, v67
	s_waitcnt lgkmcnt(0)
	v_pk_mul_f32 v[72:73], v[68:69], v[64:65]
	v_mul_f32_e32 v79, v180, v79
	v_mul_f32_e32 v64, v73, v64
	v_cndmask_b32_e32 v64, v73, v64, vcc
	v_mul_f32_e32 v65, v87, v64
	v_mul_f32_e32 v64, v85, v64
	v_mul_f32_e32 v67, v86, v64
	v_mul_f32_e32 v64, v81, v64
	v_mul_f32_e32 v68, v82, v64
	v_mul_f32_e32 v64, v83, v64
	v_mul_f32_e32 v66, v88, v66
	v_mul_f32_e32 v64, v84, v64
	v_cvt_pk_bf16_f32 v64, v64, v68
	v_cvt_pk_bf16_f32 v65, v67, v65
	v_cvt_pk_bf16_f32 v66, v66, v70
	v_cvt_pk_bf16_f32 v67, v90, v92
	v_cvt_pk_bf16_f32 v68, v91, v80
	v_cvt_pk_bf16_f32 v69, v75, v74
	v_cvt_pk_bf16_f32 v70, v77, v78
	v_cvt_pk_bf16_f32 v71, v76, v79
	v_mul_f32_e32 v177, v72, v73
	s_waitcnt vmcnt(12)
	s_setprio 1
	v_mfma_f32_32x32x16_bf16 v[48:63], v[158:161], v[64:67], v[48:63]
	v_cmp_gt_f32_e64 s[42:43], s1, v177
	s_or_b64 s[92:93], s[92:93], exec
	s_mov_b64 s[44:45], -1
	s_cmp_lg_u64 s[42:43], exec
	v_mfma_f32_32x32x16_bf16 v[32:47], v[150:153], v[64:67], v[32:47]
	s_waitcnt vmcnt(11)
	v_mfma_f32_32x32x16_bf16 v[16:31], v[146:149], v[64:67], v[16:31]
	s_waitcnt vmcnt(9)
	v_mfma_f32_32x32x16_bf16 v[0:15], v[134:137], v[64:67], v[0:15]
	v_mfma_f32_32x32x16_bf16 v[48:63], v[154:157], v[68:71], v[48:63]
	v_mfma_f32_32x32x16_bf16 v[32:47], v[142:145], v[68:71], v[32:47]
	v_mfma_f32_32x32x16_bf16 v[16:31], v[138:141], v[68:71], v[16:31]
	s_waitcnt vmcnt(8)
	v_mfma_f32_32x32x16_bf16 v[0:15], v[130:133], v[68:71], v[0:15]
	s_setprio 0
	s_cbranch_scc1 .LBB0_117
	s_branch .LBB0_118
